# att-phase extras 1/3 with scan WGs 1
# baseline (speedup 1.0000x reference)
; __global__ void __launch_bounds__(NWAVES * 64, 2) mega_fwd(Args A) {
;     ...
;     float* X = (float*)(ws + WS_X); bf16* H = (bf16*)(ws + WS_H); bf16* ACT = (bf16*)(ws + WS_ACT); bf16* PROJ = (bf16*)(ws + WS_PROJ);
;     bf16* Y = (bf16*)(ws + WS_Y); float* MACC = (float*)(ws + WS_MACC); bf16* MB = (bf16*)(ws + WS_MB); float* GO = (float*)(ws + WS_GO);
;     const float* COS = (const float*)(ws + WS_ROPE); const float* SIN = COS + (size_t)NTOK * 32;
;     { int t_ = threadIdx.x; asm volatile("" : "+v"(t_)); const int w_ = __builtin_amdgcn_readfirstlane(t_ >> 6); p0_prologue(A, lds, bx * NWAVES + w_, G * NWAVES, w_, t_ & 63); }
;     conv_until(A, lds, TL_WO1, 0);
;     xcd_barrier(bar);
; #pragma unroll 1
;     for (int step = 0; step < 3 * DEPTH; ++step) {
;         const int l = step / 3, kind = step - 3 * l;
;         unsigned char* wl = ws + WS_W + (size_t)l * LW_END;
;         const unsigned long long* ssq = (const unsigned long long*)(ws + WS_CTL + CTL_SSQ) + (size_t)step * NTOK; unsigned long long* ssq_next = (unsigned long long*)(ws + WS_CTL + CTL_SSQ) + (size_t)(step + 1) * NTOK;
;         if (kind != 1) {
;             { pg8::Gemm g{H, (const bf16*)(wl + (kind == 0 ? LW_WI1 : LW_WI2)), NTOK, NWI, DM}; pg8::StaticOrder S; S.init(NTOK, NWI, G, bx);
;               pg8::EpiSwiglu E{ACT, DFF, ssq};
;               pg8::gemm_phase<pg8::EpiSwiglu, pg8::StaticOrder, true, true>(lds + RING_OFF, g, S, E); }
;             { const int rem1 = ((NTOK / 256) * (NWI / 256)) % G;
;               conv_until(A, lds, l * TL_LAYER + (kind == 0 ? TL_WIN : TL_LAYER), (rem1 != 0 && bx >= rem1) ? 3 : 0); }
;             xcd_barrier(bar);
;         } else {
;             const bool std256 = (G == 256);
;             unsigned char* XB8 = ws + WS_X;
; #pragma unroll 1
;             for (int part = 0; part < 3; ++part) {
;                 bool do16, do8; int i16, n16, g8, c8, i8, n8;
;                 if (std256) { do16 = part == 0 || (part == 1 && bx < 64); i16 = part ? 2 : 0; n16 = part ? 1 : 2;
;                               do8 = (part == 1 && bx >= 64) || (part == 2 && bx < 128); g8 = part == 1 ? 192 : 128; c8 = part == 1 ? bx - 64 : bx; i8 = part == 1 ? 0 : 3; n8 = part == 1 ? 2 : 3; }
;                 else { do16 = part == 0; i16 = 0; n16 = 1 << 20; do8 = part == 1; g8 = G; c8 = bx; i8 = 0; n8 = 1 << 20; }
.LBB0_284:
	v_writelane_b32 v252, s64, 42
	s_nop 1
	v_writelane_b32 v252, s65, 43
	v_writelane_b32 v252, s66, 44
	v_writelane_b32 v252, s67, 45
	v_writelane_b32 v252, s68, 46
	v_writelane_b32 v252, s69, 47
	v_writelane_b32 v252, s70, 48
	v_writelane_b32 v252, s71, 49
	v_writelane_b32 v252, s72, 50
	v_writelane_b32 v252, s73, 51
	v_writelane_b32 v252, s74, 52
	v_writelane_b32 v252, s75, 53
	v_writelane_b32 v252, s76, 54
	v_writelane_b32 v252, s77, 55
	v_writelane_b32 v252, s78, 56
	v_writelane_b32 v252, s79, 57
	s_or_b64 exec, exec, s[0:1]
	s_cmpk_lg_i32 s95, 0x100
	s_cselect_b64 s[0:1], -1, 0
	s_and_b64 s[0:1], s[0:1], exec
	s_cselect_b32 s69, s95, 0x80
	s_add_i32 s4, s97, 0xffffff80
	s_cmpk_lg_i32 s95, 0x100
	s_cselect_b64 s[0:1], -1, 0
	s_and_b64 s[2:3], s[0:1], exec
	s_cselect_b32 s20, s97, s4
	v_readlane_b32 s4, v252, 2
	v_readlane_b32 s18, v252, 16
	v_readlane_b32 s19, v252, 17
	s_add_u32 s74, s18, 0x10000
	s_addc_u32 s2, s19, 0
	v_readlane_b32 s5, v252, 3
	v_readlane_b32 s6, v252, 4
	v_readlane_b32 s7, v252, 5
	v_readlane_b32 s8, v252, 6
	v_readlane_b32 s9, v252, 7
	v_readlane_b32 s10, v252, 8
	v_readlane_b32 s11, v252, 9
	v_readlane_b32 s12, v252, 10
	v_readlane_b32 s13, v252, 11
	v_readlane_b32 s14, v252, 12
	v_readlane_b32 s15, v252, 13
	v_readlane_b32 s16, v252, 14
	v_readlane_b32 s17, v252, 15
	v_writelane_b32 v252, s2, 58
	s_add_u32 s2, s18, 0x35e00000
	s_addc_u32 s3, s19, 0
	s_add_u32 s88, s18, 0x3b600000
	s_addc_u32 s89, s19, 0
	v_writelane_b32 v252, s2, 59
	s_add_u32 s12, s18, 0x45e00000
	s_addc_u32 s13, s19, 0
	v_writelane_b32 v252, s3, 60
	v_writelane_b32 v252, s12, 61
	s_add_u32 s2, s18, 0x4c200000
	v_writelane_b32 v252, s13, 62
	s_addc_u32 s3, s19, 0
	v_writelane_b32 v252, s2, 63
	s_waitcnt vmcnt(15)
	v_mov_b32_e32 v3, 0
	v_mov_b32_e32 v216, 1
	v_writelane_b32 v253, s3, 0
	s_add_u32 s2, s18, 0x4e200000
	s_addc_u32 s3, s19, 0
	v_writelane_b32 v253, s2, 1
	v_mov_b32_e32 v217, 0x7f7f7f7f
	v_mov_b32_e32 v225, 0x43e00000
	v_writelane_b32 v253, s3, 2
	s_add_u32 s2, s18, 0x4fa00000
	s_addc_u32 s3, s19, 0
	v_writelane_b32 v253, s2, 3
	v_mov_b64_e32 v[226:227], 0x2ff
	v_mov_b32_e32 v222, 0x41b17218
	v_writelane_b32 v253, s3, 4
	s_add_u32 s2, s18, 0x4fb00000
	s_addc_u32 s3, s19, 0
	v_writelane_b32 v253, s2, 5
	v_mbcnt_hi_u32_b32 v223, -1, v76
	v_mov_b32_e32 v224, 0xf149f2ca
	v_writelane_b32 v253, s3, 6
	s_add_u32 s2, s18, 0x200000
	v_writelane_b32 v253, s2, 7
	s_addc_u32 s2, s19, 0
	s_cmpk_lt_i32 s97, 0x580
	v_writelane_b32 v253, s2, 8
	s_cselect_b64 s[2:3], -1, 0
	v_writelane_b32 v253, s2, 9
	s_ashr_i32 s21, s97, 31
	s_movk_i32 s75, 0xc0
	v_writelane_b32 v253, s3, 10
	s_lshr_b32 s2, s21, 29
	s_add_i32 s3, s97, s2
	s_ashr_i32 s2, s3, 3
	s_and_b32 s3, s3, -8
	s_sub_i32 s5, s97, s3
	s_ashr_i32 s3, s95, 31
	s_add_u32 s6, s18, 0x4200
	v_writelane_b32 v253, s3, 11
	s_addc_u32 s7, s19, 0
	v_writelane_b32 v253, s6, 12
	s_movk_i32 s76, 0x300
	s_movk_i32 s77, 0x5400
	v_writelane_b32 v253, s7, 13
	s_add_u32 s6, s18, 0x4400
	s_addc_u32 s7, s19, 0
	v_writelane_b32 v253, s6, 14
	s_movk_i32 s81, 0x7fff
	s_mov_b32 s82, 0xffff0000
	v_writelane_b32 v253, s7, 15
	s_add_u32 s6, s18, 0x4500
	s_addc_u32 s7, s19, 0
	v_writelane_b32 v253, s6, 16
	s_movk_i32 s61, 0x1110
	s_movk_i32 s84, 0x15ff
	v_writelane_b32 v253, s7, 17
	s_add_u32 s6, s18, 0x4600
	s_addc_u32 s7, s19, 0
	v_writelane_b32 v253, s6, 18
	s_mov_b32 s85, 0xc3e00000
	s_movk_i32 s33, 0xff
	v_writelane_b32 v253, s7, 19
	s_add_u32 s6, s18, 0x4700
	s_addc_u32 s7, s19, 0
	v_writelane_b32 v253, s6, 20
	s_movk_i32 s66, 0x90
	s_mov_b32 s96, 0x2aaaaaab
	v_writelane_b32 v253, s7, 21
	s_add_u32 s6, s18, 0x4800
	s_addc_u32 s7, s19, 0
	v_writelane_b32 v253, s6, 22
	s_movk_i32 s36, 0x190
	s_movk_i32 s37, 0xff40
	v_writelane_b32 v253, s7, 23
	s_add_u32 s6, s18, 0x4900
	s_addc_u32 s7, s19, 0
	v_writelane_b32 v253, s6, 24
	s_movk_i32 s38, 0x567
	s_movk_i32 s39, 0x1500
	v_writelane_b32 v253, s7, 25
	s_add_u32 s6, s18, 0x4a00
	s_addc_u32 s7, s19, 0
	v_writelane_b32 v253, s6, 26
	s_movk_i32 s56, 0x1800
	s_movk_i32 s57, 0xc80
	v_writelane_b32 v253, s7, 27
	s_add_u32 s6, s18, 0x4b00
	s_addc_u32 s7, s19, 0
	v_writelane_b32 v253, s6, 28
	s_movk_i32 s58, 0x3ff
	s_mov_b32 s80, 0xefa18f08
	v_writelane_b32 v253, s7, 29
	s_add_u32 s6, s18, 0x4c00
	s_addc_u32 s7, s19, 0
	v_writelane_b32 v253, s6, 30
	s_mov_b32 s62, 0
	s_mov_b32 s94, 0x3e000000
	v_writelane_b32 v253, s7, 31
	s_add_u32 s6, s18, 0x4d00
	s_addc_u32 s7, s19, 0
	v_writelane_b32 v253, s6, 32
	s_waitcnt lgkmcnt(0)
	s_barrier
; __global__ void __launch_bounds__(NWAVES * 64, 2) mega_fwd(Args A) {
;     ...
;                 if (std256) { do16 = part == 0 || (part == 1 && bx < 64); i16 = part ? 2 : 0; n16 = part ? 1 : 2;
;                               do8 = (part == 1 && bx >= 64) || (part == 2 && bx < 128); g8 = part == 1 ? 192 : 128; c8 = part == 1 ? bx - 64 : bx; i8 = part == 1 ? 0 : 3; n8 = part == 1 ? 2 : 3; }
;                 else { do16 = part == 0; i16 = 0; n16 = 1 << 20; do8 = part == 1; g8 = G; c8 = bx; i8 = 0; n8 = 1 << 20; }
;                 if (do16) { pg8::Gemm g{H, (const bf16*)(wl + LW_WIN), NTOK, C_GATE, DM}; pg8::RangeOrder S; S.init(NTOK, C_GATE, G, bx); S.i0 = i16; S.n = n16;
;                     pg8::EpiProj E{PROJ, NPROJ, (const float*)A.in[7] + (size_t)l * 6144, 1 << 20, ssq, 1.0f};
;                     pg8::gemm_phase<pg8::EpiProj, pg8::RangeOrder, true, true>(lds + RING_OFF, g, S, E); }
;                 if (do8) { pg8::Gemm g{(const bf16*)XB8, (const bf16*)(wl + LW_WIN + WIN8_OFF), NTOK, 6144, DM / 2}; pg8::RangeOrder S; S.init(NTOK, 6144, g8, c8); S.i0 = i8; S.n = n8;
;                     pg8::EpiGate8 E{(unsigned char*)(PROJ + C_GATE), NPROJ * 2, (const float*)A.in[7] + (size_t)l * 6144, ssq, 1.0f / 2048.0f};
;                     pg8::gemm_phase<pg8::EpiGate8, pg8::RangeOrder, true, true, true>(lds + RING_OFF, g, S, E); }
;                 if (part == 1) xcd_barrier(bar);
;                 if (part == 2 && (!std256 || bx >= 128)) { const int mb = std256 ? bx - 128 : bx, ms = std256 ? 128 : G;
;                     if ((ms & 3) == 0) pool_units(lds, PROJ, (const bf16*)(ws + WS_WPT) + (size_t)l * 4 * 192 * 192, Y + (size_t)NTOK * BRW, mb, ms, 512);
;                     else for (int u = mb; u < 512; u += ms) pool_units(lds, PROJ, (const bf16*)(ws + WS_WPT) + (size_t)l * 4 * 192 * 192, Y + (size_t)NTOK * BRW, u, 512, 512);
;                     gla_pre_items(lds, PROJ, (const float*)A.in[11] + (size_t)l * 16 * 384, (const float*)A.in[12] + l * 384, ws + WS_GPRE, mb, ms, 512); }
;             }
;             xcd_barrier(bar);
;             if (G > 96) { if (bx < 48) gla_scan_unit(lds, ws + WS_GPRE, GO, bx);
;                           else for (int u = bx - 48; u < 256; u += G - 48) att_unit(lds, PROJ, COS, SIN, (const float*)A.in[8] + l * 12, Y, u); }
;             else { for (int u = bx; u < 48; u += G) gla_scan_unit(lds, ws + WS_GPRE, GO, u);
	v_writelane_b32 v253, s7, 33
	s_add_u32 s6, s18, 0x4e00
	s_addc_u32 s7, s19, 0
	v_writelane_b32 v253, s6, 34
	s_nop 1
	v_writelane_b32 v253, s7, 35
	s_add_u32 s6, s18, 0x4f00
	s_addc_u32 s7, s19, 0
	v_writelane_b32 v253, s6, 36
	s_nop 1
	v_writelane_b32 v253, s7, 37
	s_add_u32 s6, s18, 0x5000
	s_addc_u32 s7, s19, 0
	v_writelane_b32 v253, s6, 38
	s_nop 1
	v_writelane_b32 v253, s7, 39
	s_add_u32 s6, s18, 0x5100
	s_addc_u32 s7, s19, 0
	v_writelane_b32 v253, s6, 40
	s_nop 1
	v_writelane_b32 v253, s7, 41
	s_add_u32 s6, s18, 0x5200
	s_addc_u32 s7, s19, 0
	v_writelane_b32 v253, s6, 42
	s_nop 1
	v_writelane_b32 v253, s7, 43
	s_add_u32 s6, s18, 0x5300
	s_addc_u32 s7, s19, 0
	v_writelane_b32 v253, s6, 44
	s_nop 1
	v_writelane_b32 v253, s7, 45
	s_add_u32 s6, s18, 0x7400
	s_addc_u32 s7, s19, 0
	v_writelane_b32 v253, s6, 46
	s_nop 1
	v_writelane_b32 v253, s7, 47
	s_add_u32 s6, s18, 0x7500
	s_addc_u32 s7, s19, 0
	v_writelane_b32 v253, s6, 48
	s_cmpk_eq_i32 s95, 0x100
	s_nop 0
	v_writelane_b32 v253, s7, 49
	s_cselect_b64 s[6:7], -1, 0
	s_add_u32 s72, s18, 0x2fe00000
	s_addc_u32 s73, s19, 0
	v_writelane_b32 v253, s6, 50
	s_cmp_lt_i32 s97, 64
	s_nop 0
	v_writelane_b32 v253, s7, 51
	s_cselect_b64 s[6:7], -1, 0
	v_writelane_b32 v253, s6, 52
	s_cmp_gt_i32 s97, 63
	s_nop 0
	v_writelane_b32 v253, s7, 53
	s_cselect_b64 s[6:7], -1, 0
	v_writelane_b32 v253, s6, 54
	s_cmpk_lt_i32 s97, 0x80
	s_nop 0
	v_writelane_b32 v253, s7, 55
	s_cselect_b64 s[6:7], -1, 0
	v_writelane_b32 v253, s6, 56
	s_sub_i32 s3, s97, 64
	s_nop 0
	v_writelane_b32 v253, s7, 57
	s_add_u32 s6, s18, 0x3b602400
	v_writelane_b32 v253, s3, 58
	s_addc_u32 s7, s19, 0
	v_writelane_b32 v253, s6, 59
	s_cmpk_gt_i32 s97, 0x7f
	s_nop 0
	v_writelane_b32 v253, s7, 60
	s_cselect_b64 s[6:7], -1, 0
	s_or_b64 s[0:1], s[6:7], s[0:1]
	v_writelane_b32 v253, s0, 61
	s_nop 1
	v_writelane_b32 v253, s1, 62
	s_and_b32 s0, s69, 3
	s_cmp_lg_u32 s0, 0
	s_cselect_b64 s[0:1], -1, 0
	v_writelane_b32 v253, s0, 63
	s_cmpk_lt_i32 s20, 0x200
	s_nop 0
	v_writelane_b32 v254, s1, 0
	s_cselect_b64 s[0:1], -1, 0
	v_writelane_b32 v254, s0, 1
	s_nop 1
	v_writelane_b32 v254, s1, 2
	s_add_u32 s0, s18, 0x46a00000
	s_addc_u32 s1, s19, 0
	v_writelane_b32 v254, s0, 3
	s_and_b32 s4, s20, 3
	s_nop 0
	v_writelane_b32 v254, s1, 4
	s_mul_i32 s0, s4, 0x12000
	s_add_u32 s0, s34, s0
	v_writelane_b32 v254, s0, 5
	v_writelane_b32 v254, s34, 6
	s_addc_u32 s0, s35, 0
	s_lshl_b32 s68, 2, s4
	v_writelane_b32 v254, s35, 7
	v_writelane_b32 v254, s0, 8
	s_lshl_b32 s1, s20, 4
	s_lshl_b32 s0, s69, 4
	s_add_u32 s22, s18, 0x4fc00000
	v_writelane_b32 v254, s0, 9
	s_addc_u32 s23, s19, 0
	s_lshl_b32 s0, s20, 6
	s_and_b32 s0, s0, 0x7c0
	v_writelane_b32 v254, s1, 10
	s_and_b32 s1, s1, 0xfffff800
	s_or_b32 s0, s1, s0
	s_ashr_i32 s1, s0, 31
	v_writelane_b32 v254, s0, 11
	s_bfe_u32 s3, s20, 0x20005
	s_mov_b32 s35, 0
	v_writelane_b32 v254, s1, 12
	s_mul_i32 s0, s3, 0x60
	v_writelane_b32 v254, s20, 13
	s_add_i32 s1, s0, 0x920
	v_writelane_b32 v254, s1, 14
	v_writelane_b32 v254, s0, 15
	s_bitset1_b32 s0, 11
	s_cmpk_lt_i32 s95, 0x61
	v_writelane_b32 v254, s0, 16
	s_cselect_b64 s[0:1], -1, 0
	s_cmpk_gt_i32 s95, 0x60
	v_writelane_b32 v254, s0, 17
	s_cselect_b64 s[6:7], -1, 0
	s_cmp_lt_i32 s97, 48
	v_writelane_b32 v254, s1, 18
	s_cselect_b64 s[0:1], -1, 0
	v_writelane_b32 v254, s0, 19
	s_cmpk_lt_i32 s97, 0x100
	s_nop 0
	v_writelane_b32 v254, s1, 20
	s_cselect_b64 s[0:1], -1, 0
	v_writelane_b32 v254, s0, 21
	s_nop 1
	v_writelane_b32 v254, s1, 22
	s_sub_i32 s0, s97, 48
	v_writelane_b32 v254, s0, 23
	s_cmpk_lt_i32 s97, 0x130
	s_mul_hi_i32 s0, s97, 0x55555556
	s_cselect_b64 s[8:9], -1, 0
	s_lshr_b32 s1, s0, 31
	s_add_i32 s10, s0, s1
	s_mul_i32 s0, s10, -3
	s_add_i32 s0, s0, s97
	v_writelane_b32 v254, s8, 24
	s_lshl_b32 s1, s0, 13
	s_add_i32 s1, s1, 0x8000
	v_writelane_b32 v254, s9, 25
	v_writelane_b32 v254, s1, 26
	s_sub_i32 s1, s95, 48
	v_writelane_b32 v254, s1, 27
	s_lshl_b32 s8, s10, 5
	s_mul_i32 s1, s10, 0x1c4000
	v_writelane_b32 v254, s8, 28
	s_mul_hi_i32 s8, s8, 0xe200
	s_add_u32 s14, s22, s1
	s_addc_u32 s15, s23, s8
	s_add_u32 s8, s14, 0xe000
	v_writelane_b32 v254, s14, 29
	s_addc_u32 s9, s15, 0
	s_lshl_b32 s1, s10, 9
	s_lshl_b32 s0, s0, 6
	v_writelane_b32 v254, s15, 30
	s_and_b32 s11, s1, 0xfffff800
	s_ashr_i32 s1, s0, 31
	v_writelane_b32 v254, s8, 31
	s_cmp_gt_i32 s97, 47
	s_nop 0
	v_writelane_b32 v254, s9, 32
	s_cselect_b64 s[8:9], -1, 0
	v_writelane_b32 v254, s8, 33
	s_mov_b64 s[14:15], s[6:7]
	s_add_i32 s6, s97, s95
	s_addk_i32 s6, 0xffa0
	v_writelane_b32 v254, s9, 34
	s_cmpk_lt_i32 s6, 0x100
	s_cselect_b32 s8, 1, 3
	v_writelane_b32 v254, s14, 35
	s_and_b64 s[6:7], s[14:15], exec
	s_cselect_b32 s6, s8, 0
	v_writelane_b32 v254, s15, 36
	v_writelane_b32 v254, s6, 37
	s_add_u32 s6, s18, 0x47600000
	v_writelane_b32 v254, s6, 38
	s_addc_u32 s6, s19, 0
	v_writelane_b32 v254, s6, 39
	s_lshl_b32 s14, s95, 5
	s_lshl_b32 s6, s5, 5
	s_cmp_lt_i32 s5, 0
	s_movk_i32 s7, 0xb1
;     __host__ __device__ bool next(int i, Unit& u) const {
;         const long L = (long)i * G + c; if (L >= nwg) return false;
;         int wgid = (int)L; { const int q = nwg / NXCD, r = nwg % NXCD, xcd = wgid % NXCD, off = wgid / NXCD; wgid = (xcd < r ? xcd * (q + 1) : r * (q + 1) + (xcd - r) * q) + off; }
;         const int nig = WGM * nN, gid = wgid / nig, fm = gid * WGM, gsz = (nM - fm) < WGM ? (nM - fm) : WGM;
;         u.pm = fm + ((wgid % nig) % gsz); u.pn = (wgid % nig) / gsz; u.seg = 0; return true;
; __global__ void __launch_bounds__(NWAVES * 64, 2) mega_fwd(Args A) {
;     ...
;             { const int rem1 = ((NTOK / 256) * (NWI / 256)) % G;
;               conv_until(A, lds, l * TL_LAYER + (kind == 0 ? TL_WIN : TL_LAYER), (rem1 != 0 && bx >= rem1) ? 3 : 0); }
	s_cselect_b32 s7, s7, 0xb0
	s_mul_i32 s7, s5, s7
	s_mul_i32 s5, s5, 33
	s_cselect_b32 s5, s5, s6
	s_add_i32 s7, s7, s2
	s_mul_hi_i32 s6, s7, 0x2e8ba2e9
	s_lshr_b32 s8, s6, 31
	s_ashr_i32 s6, s6, 6
	s_add_i32 s6, s6, s8
	s_mul_i32 s8, s6, 0x160
	s_sub_i32 s7, s7, s8
	s_bfe_u32 s8, s7, 0x3001c
	s_add_i32 s8, s7, s8
	s_and_b32 s9, s8, 0xfff8
	s_sub_i32 s7, s7, s9
	s_lshl_b32 s6, s6, 3
	s_sext_i32_i16 s8, s8
	s_sext_i32_i16 s7, s7
	s_add_i32 s16, s6, s7
	s_ashr_i32 s6, s8, 3
	v_writelane_b32 v254, s6, 40
	s_lshr_b32 s6, s8, 3
	s_bfe_i64 s[6:7], s[6:7], 0x100000
	s_lshl_b64 s[6:7], s[6:7], 20
	v_writelane_b32 v254, s6, 41
	s_ashr_i32 s17, s16, 31
	s_nop 0
	v_writelane_b32 v254, s7, 42
	s_mov_b32 s6, s16
	v_writelane_b32 v254, s6, 43
	s_nop 1
	v_writelane_b32 v254, s7, 44
	s_lshl_b64 s[6:7], s[16:17], 20
	s_add_u32 s6, s90, s6
	s_addc_u32 s7, s91, s7
	s_add_u32 s8, s6, 0x80000
	s_addc_u32 s9, s7, 0
	v_writelane_b32 v254, s8, 45
	s_nop 1
	v_writelane_b32 v254, s9, 46
	s_add_u32 s8, s6, 0x2000
	v_writelane_b32 v254, s6, 47
	s_addc_u32 s9, s7, 0
	s_add_i32 s2, s5, s2
	s_ashr_i32 s5, s2, 31
	s_lshr_b32 s5, s5, 26
	s_add_i32 s5, s2, s5
	v_writelane_b32 v254, s7, 48
	s_and_b32 s6, s5, 0xffc0
	s_sub_i32 s2, s2, s6
	s_bfe_i32 s6, s2, 0x80000
	s_bfe_u32 s6, s6, 0x3000c
	s_add_i32 s6, s2, s6
	s_and_b32 s7, s6, 0xf8
	s_sub_i32 s2, s2, s7
	s_ashr_i32 s5, s5, 6
	s_lshl_b32 s5, s5, 3
	s_sext_i32_i8 s2, s2
	s_add_i32 s5, s5, s2
	s_bfe_i32 s2, s6, 0x80000
	v_writelane_b32 v254, s8, 49
	s_sext_i32_i16 s2, s2
	s_ashr_i32 s6, s2, 3
	v_writelane_b32 v254, s9, 50
	s_lshr_b32 s2, s2, 3
	v_writelane_b32 v254, s6, 51
	s_bfe_i64 s[6:7], s[2:3], 0x100000
	v_writelane_b32 v254, s6, 52
	s_mul_hi_i32 s2, s5, 0x60000
	s_nop 0
	v_writelane_b32 v254, s7, 53
	v_writelane_b32 v254, s5, 54
	s_mul_i32 s5, s5, 0x60000
	s_add_u32 s6, s12, s5
	s_addc_u32 s7, s13, s2
	s_add_u32 s8, s6, 0x30000
	s_addc_u32 s9, s7, 0
	v_writelane_b32 v254, s8, 55
	s_nop 1
	v_writelane_b32 v254, s9, 56
	s_add_u32 s8, s6, 0x2000
	v_writelane_b32 v254, s6, 57
	s_addc_u32 s9, s7, 0
	s_abs_i32 s2, s95
	v_cvt_f32_u32_e32 v1, s2
	v_writelane_b32 v254, s7, 58
	s_sub_i32 s5, 0, s2
	v_writelane_b32 v254, s8, 59
	v_rcp_iflag_f32_e32 v1, v1
	s_nop 0
	v_writelane_b32 v254, s9, 60
	v_mul_f32_e32 v1, 0x4f7ffffe, v1
	v_cvt_u32_f32_e32 v1, v1
	s_nop 0
	v_readfirstlane_b32 s6, v1
	s_mul_i32 s5, s5, s6
	s_mul_hi_u32 s5, s6, s5
	s_add_i32 s6, s6, s5
	s_mul_hi_u32 s5, s6, 0x580
	s_mul_i32 s5, s5, s2
	s_sub_i32 s5, 0x580, s5
	s_sub_i32 s6, s5, s2
	s_cmp_ge_u32 s5, s2
	s_cselect_b32 s5, s6, s5
	s_sub_i32 s6, s5, s2
	s_cmp_ge_u32 s5, s2
	s_cselect_b32 s2, s6, s5
	s_cmp_lg_u32 s2, 0
	s_cselect_b64 s[6:7], -1, 0
	s_cmp_ge_i32 s97, s2
	s_cselect_b64 s[8:9], -1, 0
	s_and_b64 s[6:7], s[6:7], s[8:9]
	s_mul_i32 s2, s4, 0xc0
	v_writelane_b32 v254, s6, 61
	s_and_b64 s[4:5], s[6:7], exec
	s_cselect_b32 s4, 3, 0
	v_writelane_b32 v254, s7, 62
	v_writelane_b32 v255, s2, 0
	s_lshl_b32 s2, s2, 1
	v_writelane_b32 v254, s4, 63
	s_add_u32 s4, s88, s2
	s_addc_u32 s5, s89, 0
	v_writelane_b32 v255, s4, 1
	s_and_b32 s2, s10, 3
	s_mulk_i32 s2, 0x300
	v_writelane_b32 v255, s5, 2
	s_mul_i32 s4, s11, 0xc00
	s_lshl_b32 s5, s97, 6
	s_or_b32 s2, s4, s2
	s_lshl_b64 s[0:1], s[0:1], 2
	v_writelane_b32 v255, s5, 3
	s_lshl_b32 s5, s95, 6
	s_mul_hi_i32 s4, s11, 0xc00
	s_add_u32 s0, s2, s0
	s_addc_u32 s1, s4, s1
	s_add_u32 s0, s18, s0
	v_writelane_b32 v255, s5, 4
	s_addc_u32 s1, s19, s1
	v_writelane_b32 v255, s0, 5
	s_mul_i32 s2, s95, 0x18000
	s_add_i32 s93, 0, 0x20180
	v_writelane_b32 v255, s1, 6
	s_mul_i32 s0, s3, 0xc0
	s_mul_hi_i32 s3, s14, 0xc00
	v_writelane_b32 v255, s2, 7
	s_lshl_b32 s1, s97, 9
	s_lshl_b32 s0, s0, 1
	v_writelane_b32 v255, s3, 8
	s_mul_i32 s2, s95, 0xa8000
	v_writelane_b32 v255, s14, 9
	s_mul_hi_i32 s3, s14, 0x5400
	v_writelane_b32 v255, s2, 10
	s_add_i32 s60, 0, 0x20184
	v_mov_b32_e32 v1, 0x358637bd
	v_writelane_b32 v255, s3, 11
	v_writelane_b32 v255, s1, 12
	s_lshl_b32 s1, s95, 11
	v_writelane_b32 v255, s1, 13
	s_lshl_b32 s1, s95, 4
	v_writelane_b32 v255, s1, 14
	s_lshl_b32 s1, s95, 10
	v_writelane_b32 v255, s1, 15
	s_lshl_b32 s1, s95, 9
	v_writelane_b32 v255, s1, 16
	s_add_i32 s1, 0, 0x20160
	v_writelane_b32 v255, s1, 17
	s_add_i32 s1, 0, 0x20164
	v_writelane_b32 v255, s1, 18
	s_add_i32 s1, 0, 0x2d00
	v_writelane_b32 v255, s1, 19
	v_writelane_b32 v255, s0, 20
	s_add_i32 s64, 0, 0x12600
	s_nop 0
	v_writelane_b32 v255, s1, 21
	s_add_i32 s0, 0, 0xf000
	v_writelane_b32 v255, s0, 22
	s_add_i32 s0, 0, 0x8800
	v_writelane_b32 v255, s0, 23
	v_writelane_b32 v255, s90, 24
	s_nop 1
	v_writelane_b32 v255, s91, 25
	v_writelane_b32 v255, s69, 26
	v_writelane_b32 v255, s88, 27
	s_nop 1
	v_writelane_b32 v255, s89, 28
	v_writelane_b32 v255, s21, 29
	v_writelane_b32 v255, s22, 30
	v_writelane_b32 v255, s23, 31
	v_writelane_b32 v255, s93, 32
	v_writelane_b32 v255, s60, 33
	v_writelane_b32 v255, s92, 34
	s_nop 1
	v_writelane_b32 v255, s93, 35
	s_branch .LBB0_287
